# GEMM K-loops: loop-control SALU rotated ahead of the loop-back barrier (sec 7.11)
# speedup vs baseline: 1.0074x; 1.0074x over previous
.LBB0_127:
	s_add_u32 s48, s46, 0xfff80080
	s_addc_u32 s49, s47, -1
	s_add_i32 s77, 0, 0x10000
	s_cmp_eq_u32 s76, 28
	s_cselect_b32 s51, s41, s49
	s_cselect_b32 s50, s64, s48
	s_cselect_b32 s49, s39, s67
	s_cselect_b32 s48, s65, s66
	s_add_i32 vcc_lo, 0, 0x14000
	v_add_u32_e32 v154, s77, v182
	v_add_u32_e32 v170, vcc_lo, v182
	ds_read_b128 v[142:145], v154
	ds_read_b128 v[146:149], v154 offset:1024
	ds_read_b128 v[150:153], v154 offset:2048
	ds_read_b128 v[154:157], v154 offset:3072
	ds_read_b128 v[158:161], v170
	ds_read_b128 v[162:165], v170 offset:1024
	ds_read_b128 v[166:169], v170 offset:2048
	ds_read_b128 v[170:173], v170 offset:3072
	v_lshl_add_u64 v[174:175], s[46:47], 0, v[138:139]
	s_add_i32 m0, s55, 0xc000
	ds_read_b128 v[178:181], v205
	ds_read_b128 v[208:211], v205 offset:1024
	ds_read_b128 v[212:215], v205 offset:2048
	ds_read_b128 v[216:219], v205 offset:3072
	ds_read_b128 v[220:223], v205 offset:4096
	ds_read_b128 v[224:227], v205 offset:5120
	ds_read_b128 v[228:231], v205 offset:6144
	ds_read_b128 v[232:235], v205 offset:7168
	global_load_lds_dwordx4 v[174:175], off
	v_lshl_add_u64 v[174:175], s[46:47], 0, v[140:141]
	s_add_i32 m0, s55, 0xe000
	s_nop 0
	global_load_lds_dwordx4 v[174:175], off
	s_waitcnt vmcnt(8)
	s_waitcnt lgkmcnt(0)
	s_barrier
	s_setprio 1
	s_waitcnt lgkmcnt(0)
	v_mfma_f32_16x16x32_bf16 v[126:129], v[142:145], v[178:181], v[126:129]
	v_mfma_f32_16x16x32_bf16 v[122:125], v[150:153], v[178:181], v[122:125]
	v_mfma_f32_16x16x32_bf16 v[110:113], v[142:145], v[212:215], v[110:113]
	v_mfma_f32_16x16x32_bf16 v[106:109], v[150:153], v[212:215], v[106:109]
	v_mfma_f32_16x16x32_bf16 v[94:97], v[142:145], v[220:223], v[94:97]
	v_mfma_f32_16x16x32_bf16 v[90:93], v[150:153], v[220:223], v[90:93]
	v_mfma_f32_16x16x32_bf16 v[78:81], v[142:145], v[228:231], v[78:81]
	v_mfma_f32_16x16x32_bf16 v[74:77], v[150:153], v[228:231], v[74:77]
	v_mfma_f32_16x16x32_bf16 v[126:129], v[146:149], v[208:211], v[126:129]
	v_mfma_f32_16x16x32_bf16 v[122:125], v[154:157], v[208:211], v[122:125]
	v_mfma_f32_16x16x32_bf16 v[110:113], v[146:149], v[216:219], v[110:113]
	v_mfma_f32_16x16x32_bf16 v[106:109], v[154:157], v[216:219], v[106:109]
	v_mfma_f32_16x16x32_bf16 v[94:97], v[146:149], v[224:227], v[94:97]
	v_mfma_f32_16x16x32_bf16 v[90:93], v[154:157], v[224:227], v[90:93]
	v_mfma_f32_16x16x32_bf16 v[78:81], v[146:149], v[232:235], v[78:81]
	v_mfma_f32_16x16x32_bf16 v[74:77], v[154:157], v[232:235], v[74:77]
	s_setprio 0
	s_setprio 1
	v_mfma_f32_16x16x32_bf16 v[118:121], v[158:161], v[178:181], v[118:121]
	v_mfma_f32_16x16x32_bf16 v[114:117], v[166:169], v[178:181], v[114:117]
	v_mfma_f32_16x16x32_bf16 v[102:105], v[158:161], v[212:215], v[102:105]
	v_mfma_f32_16x16x32_bf16 v[98:101], v[166:169], v[212:215], v[98:101]
	v_mfma_f32_16x16x32_bf16 v[86:89], v[158:161], v[220:223], v[86:89]
	v_mfma_f32_16x16x32_bf16 v[82:85], v[166:169], v[220:223], v[82:85]
	v_mfma_f32_16x16x32_bf16 v[70:73], v[158:161], v[228:231], v[70:73]
	v_mfma_f32_16x16x32_bf16 v[66:69], v[166:169], v[228:231], v[66:69]
	v_mfma_f32_16x16x32_bf16 v[118:121], v[162:165], v[208:211], v[118:121]
	v_mfma_f32_16x16x32_bf16 v[114:117], v[170:173], v[208:211], v[114:117]
	v_mfma_f32_16x16x32_bf16 v[102:105], v[162:165], v[216:219], v[102:105]
	v_mfma_f32_16x16x32_bf16 v[98:101], v[170:173], v[216:219], v[98:101]
	v_mfma_f32_16x16x32_bf16 v[86:89], v[162:165], v[224:227], v[86:89]
	v_mfma_f32_16x16x32_bf16 v[82:85], v[170:173], v[224:227], v[82:85]
	v_mfma_f32_16x16x32_bf16 v[70:73], v[162:165], v[232:235], v[70:73]
	v_mfma_f32_16x16x32_bf16 v[66:69], v[170:173], v[232:235], v[66:69]
	s_setprio 0
	s_barrier
	s_add_i32 s77, s77, s54
	v_lshl_add_u64 v[174:175], s[48:49], 0, v[0:1]
	s_mov_b32 m0, s77
	ds_read_b128 v[178:181], v205 offset:16384
	ds_read_b128 v[208:211], v205 offset:17408
	ds_read_b128 v[212:215], v205 offset:18432
	ds_read_b128 v[216:219], v205 offset:19456
	ds_read_b128 v[220:223], v205 offset:20480
	ds_read_b128 v[224:227], v205 offset:21504
	ds_read_b128 v[228:231], v205 offset:22528
	ds_read_b128 v[232:235], v205 offset:23552
	global_load_lds_dwordx4 v[174:175], off
	s_add_i32 m0, s77, 0x2000
	s_add_u32 s86, s48, 0x80000
	v_lshl_add_u64 v[202:203], s[48:49], 0, v[130:131]
	s_addc_u32 s87, s49, 0
	s_add_i32 s77, vcc_lo, s54
	global_load_lds_dwordx4 v[202:203], off
	v_lshl_add_u64 v[236:237], s[86:87], 0, v[0:1]
	s_mov_b32 m0, s77
	v_lshl_add_u64 v[238:239], s[50:51], 0, v[132:133]
	global_load_lds_dwordx4 v[236:237], off
	v_lshl_add_u64 v[236:237], s[86:87], 0, v[130:131]
	s_add_i32 m0, s77, 0x2000
	s_nop 0
	global_load_lds_dwordx4 v[236:237], off
	v_lshl_add_u64 v[236:237], s[50:51], 0, v[134:135]
	s_mov_b32 m0, s55
	s_nop 0
	global_load_lds_dwordx4 v[236:237], off
	s_mov_b32 m0, s56
	s_nop 0
	global_load_lds_dwordx4 v[238:239], off
	s_waitcnt vmcnt(8)
	s_waitcnt lgkmcnt(0)
	s_barrier
	s_setprio 1
	s_waitcnt lgkmcnt(0)
	v_mfma_f32_16x16x32_bf16 v[62:65], v[142:145], v[178:181], v[62:65]
	v_mfma_f32_16x16x32_bf16 v[58:61], v[150:153], v[178:181], v[58:61]
	v_mfma_f32_16x16x32_bf16 v[46:49], v[142:145], v[212:215], v[46:49]
	v_mfma_f32_16x16x32_bf16 v[42:45], v[150:153], v[212:215], v[42:45]
	v_mfma_f32_16x16x32_bf16 v[30:33], v[142:145], v[220:223], v[30:33]
	v_mfma_f32_16x16x32_bf16 v[26:29], v[150:153], v[220:223], v[26:29]
	v_mfma_f32_16x16x32_bf16 v[14:17], v[142:145], v[228:231], v[14:17]
	v_mfma_f32_16x16x32_bf16 v[10:13], v[150:153], v[228:231], v[10:13]
	v_mfma_f32_16x16x32_bf16 v[62:65], v[146:149], v[208:211], v[62:65]
	v_mfma_f32_16x16x32_bf16 v[58:61], v[154:157], v[208:211], v[58:61]
	v_mfma_f32_16x16x32_bf16 v[46:49], v[146:149], v[216:219], v[46:49]
	v_mfma_f32_16x16x32_bf16 v[42:45], v[154:157], v[216:219], v[42:45]
	v_mfma_f32_16x16x32_bf16 v[30:33], v[146:149], v[224:227], v[30:33]
	v_mfma_f32_16x16x32_bf16 v[26:29], v[154:157], v[224:227], v[26:29]
	v_mfma_f32_16x16x32_bf16 v[14:17], v[146:149], v[232:235], v[14:17]
	v_mfma_f32_16x16x32_bf16 v[10:13], v[154:157], v[232:235], v[10:13]
	s_setprio 0
	s_setprio 1
	v_mfma_f32_16x16x32_bf16 v[54:57], v[158:161], v[178:181], v[54:57]
	v_mfma_f32_16x16x32_bf16 v[50:53], v[166:169], v[178:181], v[50:53]
	v_mfma_f32_16x16x32_bf16 v[38:41], v[158:161], v[212:215], v[38:41]
	v_mfma_f32_16x16x32_bf16 v[34:37], v[166:169], v[212:215], v[34:37]
	v_mfma_f32_16x16x32_bf16 v[22:25], v[158:161], v[220:223], v[22:25]
	v_mfma_f32_16x16x32_bf16 v[18:21], v[166:169], v[220:223], v[18:21]
	v_mfma_f32_16x16x32_bf16 v[6:9], v[158:161], v[228:231], v[6:9]
	v_mfma_f32_16x16x32_bf16 v[2:5], v[166:169], v[228:231], v[2:5]
	v_mfma_f32_16x16x32_bf16 v[54:57], v[162:165], v[208:211], v[54:57]
	v_mfma_f32_16x16x32_bf16 v[50:53], v[170:173], v[208:211], v[50:53]
	v_mfma_f32_16x16x32_bf16 v[38:41], v[162:165], v[216:219], v[38:41]
	v_mfma_f32_16x16x32_bf16 v[34:37], v[170:173], v[216:219], v[34:37]
	v_mfma_f32_16x16x32_bf16 v[22:25], v[162:165], v[224:227], v[22:25]
	v_mfma_f32_16x16x32_bf16 v[18:21], v[170:173], v[224:227], v[18:21]
	v_mfma_f32_16x16x32_bf16 v[6:9], v[162:165], v[232:235], v[6:9]
	v_mfma_f32_16x16x32_bf16 v[2:5], v[170:173], v[232:235], v[2:5]
	s_setprio 0
	s_barrier
	s_add_i32 s77, 0, 0x18000
	s_add_i32 s86, 0, 0x1c000
	v_add_u32_e32 v154, s77, v182
	v_add_u32_e32 v170, s86, v182
	ds_read_b128 v[142:145], v154
	ds_read_b128 v[146:149], v154 offset:1024
	ds_read_b128 v[150:153], v154 offset:2048
	ds_read_b128 v[154:157], v154 offset:3072
	ds_read_b128 v[158:161], v170
	ds_read_b128 v[162:165], v170 offset:1024
	ds_read_b128 v[166:169], v170 offset:2048
	ds_read_b128 v[170:173], v170 offset:3072
	s_add_u32 s50, s50, 0x80000
	s_addc_u32 s51, s51, 0
	s_mov_b32 m0, s57
	v_lshl_add_u64 v[240:241], s[50:51], 0, v[134:135]
	ds_read_b128 v[178:181], v205 offset:32768
	ds_read_b128 v[208:211], v205 offset:33792
	ds_read_b128 v[212:215], v205 offset:34816
	ds_read_b128 v[216:219], v205 offset:35840
	ds_read_b128 v[220:223], v205 offset:36864
	ds_read_b128 v[224:227], v205 offset:37888
	ds_read_b128 v[228:231], v205 offset:38912
	ds_read_b128 v[232:235], v205 offset:39936
	global_load_lds_dwordx4 v[240:241], off
	v_lshl_add_u64 v[240:241], s[50:51], 0, v[132:133]
	s_mov_b32 m0, s58
	s_nop 0
	global_load_lds_dwordx4 v[240:241], off
	s_waitcnt vmcnt(8)
	s_waitcnt lgkmcnt(0)
	s_barrier
	s_setprio 1
	s_waitcnt lgkmcnt(0)
	v_mfma_f32_16x16x32_bf16 v[126:129], v[142:145], v[178:181], v[126:129]
	v_mfma_f32_16x16x32_bf16 v[122:125], v[150:153], v[178:181], v[122:125]
	v_mfma_f32_16x16x32_bf16 v[110:113], v[142:145], v[212:215], v[110:113]
	v_mfma_f32_16x16x32_bf16 v[106:109], v[150:153], v[212:215], v[106:109]
	v_mfma_f32_16x16x32_bf16 v[94:97], v[142:145], v[220:223], v[94:97]
	v_mfma_f32_16x16x32_bf16 v[90:93], v[150:153], v[220:223], v[90:93]
	v_mfma_f32_16x16x32_bf16 v[78:81], v[142:145], v[228:231], v[78:81]
	v_mfma_f32_16x16x32_bf16 v[74:77], v[150:153], v[228:231], v[74:77]
	v_mfma_f32_16x16x32_bf16 v[126:129], v[146:149], v[208:211], v[126:129]
	v_mfma_f32_16x16x32_bf16 v[122:125], v[154:157], v[208:211], v[122:125]
	v_mfma_f32_16x16x32_bf16 v[110:113], v[146:149], v[216:219], v[110:113]
	v_mfma_f32_16x16x32_bf16 v[106:109], v[154:157], v[216:219], v[106:109]
	v_mfma_f32_16x16x32_bf16 v[94:97], v[146:149], v[224:227], v[94:97]
	v_mfma_f32_16x16x32_bf16 v[90:93], v[154:157], v[224:227], v[90:93]
	v_mfma_f32_16x16x32_bf16 v[78:81], v[146:149], v[232:235], v[78:81]
	v_mfma_f32_16x16x32_bf16 v[74:77], v[154:157], v[232:235], v[74:77]
	s_setprio 0
	s_setprio 1
	v_mfma_f32_16x16x32_bf16 v[118:121], v[158:161], v[178:181], v[118:121]
	v_mfma_f32_16x16x32_bf16 v[114:117], v[166:169], v[178:181], v[114:117]
	v_mfma_f32_16x16x32_bf16 v[102:105], v[158:161], v[212:215], v[102:105]
	v_mfma_f32_16x16x32_bf16 v[98:101], v[166:169], v[212:215], v[98:101]
	v_mfma_f32_16x16x32_bf16 v[86:89], v[158:161], v[220:223], v[86:89]
	v_mfma_f32_16x16x32_bf16 v[82:85], v[166:169], v[220:223], v[82:85]
	v_mfma_f32_16x16x32_bf16 v[70:73], v[158:161], v[228:231], v[70:73]
	v_mfma_f32_16x16x32_bf16 v[66:69], v[166:169], v[228:231], v[66:69]
	v_mfma_f32_16x16x32_bf16 v[118:121], v[162:165], v[208:211], v[118:121]
	v_mfma_f32_16x16x32_bf16 v[114:117], v[170:173], v[208:211], v[114:117]
	v_mfma_f32_16x16x32_bf16 v[102:105], v[162:165], v[216:219], v[102:105]
	v_mfma_f32_16x16x32_bf16 v[98:101], v[170:173], v[216:219], v[98:101]
	v_mfma_f32_16x16x32_bf16 v[86:89], v[162:165], v[224:227], v[86:89]
	v_mfma_f32_16x16x32_bf16 v[82:85], v[170:173], v[224:227], v[82:85]
	v_mfma_f32_16x16x32_bf16 v[70:73], v[162:165], v[232:235], v[70:73]
	v_mfma_f32_16x16x32_bf16 v[66:69], v[170:173], v[232:235], v[66:69]
	s_setprio 0
	s_barrier
	s_add_i32 s50, s77, s54
	v_lshl_add_u64 v[174:175], v[174:175], 0, s[88:89]
	s_mov_b32 m0, s50
	ds_read_b128 v[178:181], v205 offset:49152
	ds_read_b128 v[208:211], v205 offset:50176
	ds_read_b128 v[212:215], v205 offset:51200
	ds_read_b128 v[216:219], v205 offset:52224
	ds_read_b128 v[220:223], v205 offset:53248
	ds_read_b128 v[224:227], v205 offset:54272
	ds_read_b128 v[228:231], v205 offset:55296
	ds_read_b128 v[232:235], v205 offset:56320
	global_load_lds_dwordx4 v[174:175], off
	s_add_i32 m0, s50, 0x2000
	s_add_u32 s48, s48, 0x80080
	v_lshl_add_u64 v[174:175], v[202:203], 0, s[88:89]
	s_addc_u32 s49, s49, 0
	s_add_i32 s50, s86, s54
	global_load_lds_dwordx4 v[174:175], off
	v_lshl_add_u64 v[174:175], s[48:49], 0, v[0:1]
	s_mov_b32 m0, s50
	s_nop 0
	global_load_lds_dwordx4 v[174:175], off
	v_lshl_add_u64 v[174:175], s[48:49], 0, v[130:131]
	s_add_i32 m0, s50, 0x2000
	s_nop 0
	global_load_lds_dwordx4 v[174:175], off
	v_lshl_add_u64 v[174:175], v[236:237], 0, s[88:89]
	s_mov_b32 m0, s59
	s_nop 0
	global_load_lds_dwordx4 v[174:175], off
	v_lshl_add_u64 v[174:175], v[238:239], 0, s[88:89]
	s_mov_b32 m0, s60
	s_nop 0
	global_load_lds_dwordx4 v[174:175], off
	s_waitcnt vmcnt(8)
	s_waitcnt lgkmcnt(0)
	s_barrier
	s_setprio 1
	s_waitcnt lgkmcnt(0)
	v_mfma_f32_16x16x32_bf16 v[62:65], v[142:145], v[178:181], v[62:65]
	v_mfma_f32_16x16x32_bf16 v[58:61], v[150:153], v[178:181], v[58:61]
	v_mfma_f32_16x16x32_bf16 v[46:49], v[142:145], v[212:215], v[46:49]
	v_mfma_f32_16x16x32_bf16 v[42:45], v[150:153], v[212:215], v[42:45]
	v_mfma_f32_16x16x32_bf16 v[30:33], v[142:145], v[220:223], v[30:33]
	v_mfma_f32_16x16x32_bf16 v[26:29], v[150:153], v[220:223], v[26:29]
	v_mfma_f32_16x16x32_bf16 v[14:17], v[142:145], v[228:231], v[14:17]
	v_mfma_f32_16x16x32_bf16 v[10:13], v[150:153], v[228:231], v[10:13]
	v_mfma_f32_16x16x32_bf16 v[62:65], v[146:149], v[208:211], v[62:65]
	v_mfma_f32_16x16x32_bf16 v[58:61], v[154:157], v[208:211], v[58:61]
	v_mfma_f32_16x16x32_bf16 v[46:49], v[146:149], v[216:219], v[46:49]
	v_mfma_f32_16x16x32_bf16 v[42:45], v[154:157], v[216:219], v[42:45]
	v_mfma_f32_16x16x32_bf16 v[30:33], v[146:149], v[224:227], v[30:33]
	v_mfma_f32_16x16x32_bf16 v[26:29], v[154:157], v[224:227], v[26:29]
	v_mfma_f32_16x16x32_bf16 v[14:17], v[146:149], v[232:235], v[14:17]
	v_mfma_f32_16x16x32_bf16 v[10:13], v[154:157], v[232:235], v[10:13]
	s_setprio 0
	s_setprio 1
	v_mfma_f32_16x16x32_bf16 v[54:57], v[158:161], v[178:181], v[54:57]
	v_mfma_f32_16x16x32_bf16 v[50:53], v[166:169], v[178:181], v[50:53]
	v_mfma_f32_16x16x32_bf16 v[38:41], v[158:161], v[212:215], v[38:41]
	v_mfma_f32_16x16x32_bf16 v[34:37], v[166:169], v[212:215], v[34:37]
	v_mfma_f32_16x16x32_bf16 v[22:25], v[158:161], v[220:223], v[22:25]
	v_mfma_f32_16x16x32_bf16 v[18:21], v[166:169], v[220:223], v[18:21]
	v_mfma_f32_16x16x32_bf16 v[6:9], v[158:161], v[228:231], v[6:9]
	v_mfma_f32_16x16x32_bf16 v[2:5], v[166:169], v[228:231], v[2:5]
	v_mfma_f32_16x16x32_bf16 v[54:57], v[162:165], v[208:211], v[54:57]
	v_mfma_f32_16x16x32_bf16 v[50:53], v[170:173], v[208:211], v[50:53]
	v_mfma_f32_16x16x32_bf16 v[38:41], v[162:165], v[216:219], v[38:41]
	v_mfma_f32_16x16x32_bf16 v[34:37], v[170:173], v[216:219], v[34:37]
	v_mfma_f32_16x16x32_bf16 v[22:25], v[162:165], v[224:227], v[22:25]
	v_mfma_f32_16x16x32_bf16 v[18:21], v[170:173], v[224:227], v[18:21]
	v_mfma_f32_16x16x32_bf16 v[6:9], v[162:165], v[232:235], v[6:9]
	v_mfma_f32_16x16x32_bf16 v[2:5], v[170:173], v[232:235], v[2:5]
	s_setprio 0
	s_add_i32 s76, s76, 2
	s_add_u32 s46, s46, 0x100
	s_addc_u32 s47, s47, 0
	s_add_u32 s66, s66, 0x100
	s_addc_u32 s67, s67, 0
	s_cmp_gt_u32 s76, 29
	s_barrier
	s_cbranch_scc0 .LBB0_127
	s_and_b64 vcc, exec, s[24:25]
	s_cbranch_vccz .LBB0_130
	s_barrier

.LBB0_578:
	s_add_u32 s50, s4, 0xfff80080
	s_addc_u32 s51, s5, -1
	s_add_i32 s86, 0, 0x10000
	s_cmp_eq_u32 s77, 28
	s_cselect_b32 s53, s45, s51
	s_cselect_b32 s52, s65, s50
	s_cselect_b32 s51, s43, s76
	s_cselect_b32 s50, s66, s67
	s_add_i32 vcc_lo, 0, 0x14000
	v_add_u32_e32 v142, s86, v188
	v_add_u32_e32 v168, vcc_lo, v188
	ds_read_b128 v[118:121], v142
	ds_read_b128 v[126:129], v142 offset:1024
	ds_read_b128 v[138:141], v142 offset:2048
	ds_read_b128 v[142:145], v142 offset:3072
	ds_read_b128 v[146:149], v168
	ds_read_b128 v[150:153], v168 offset:1024
	ds_read_b128 v[154:157], v168 offset:2048
	ds_read_b128 v[168:171], v168 offset:3072
	v_lshl_add_u64 v[186:187], s[4:5], 0, v[164:165]
	s_add_i32 m0, s57, 0xc000
	ds_read_b128 v[172:175], v190
	ds_read_b128 v[178:181], v190 offset:1024
	ds_read_b128 v[182:185], v190 offset:2048
	ds_read_b128 v[202:205], v190 offset:3072
	ds_read_b128 v[206:209], v190 offset:4096
	ds_read_b128 v[210:213], v190 offset:5120
	ds_read_b128 v[214:217], v190 offset:6144
	ds_read_b128 v[218:221], v190 offset:7168
	global_load_lds_dwordx4 v[186:187], off
	v_lshl_add_u64 v[186:187], s[4:5], 0, v[166:167]
	s_add_i32 m0, s57, 0xe000
	s_nop 0
	global_load_lds_dwordx4 v[186:187], off
	s_waitcnt vmcnt(8)
	s_waitcnt lgkmcnt(0)
	s_barrier
	s_setprio 1
	s_waitcnt lgkmcnt(0)
	v_mfma_f32_16x16x32_bf16 v[134:137], v[118:121], v[172:175], v[134:137]
	v_mfma_f32_16x16x32_bf16 v[130:133], v[138:141], v[172:175], v[130:133]
	v_mfma_f32_16x16x32_bf16 v[110:113], v[118:121], v[182:185], v[110:113]
	v_mfma_f32_16x16x32_bf16 v[106:109], v[138:141], v[182:185], v[106:109]
	v_mfma_f32_16x16x32_bf16 v[94:97], v[118:121], v[206:209], v[94:97]
	v_mfma_f32_16x16x32_bf16 v[90:93], v[138:141], v[206:209], v[90:93]
	v_mfma_f32_16x16x32_bf16 v[78:81], v[118:121], v[214:217], v[78:81]
	v_mfma_f32_16x16x32_bf16 v[74:77], v[138:141], v[214:217], v[74:77]
	v_mfma_f32_16x16x32_bf16 v[134:137], v[126:129], v[178:181], v[134:137]
	v_mfma_f32_16x16x32_bf16 v[130:133], v[142:145], v[178:181], v[130:133]
	v_mfma_f32_16x16x32_bf16 v[110:113], v[126:129], v[202:205], v[110:113]
	v_mfma_f32_16x16x32_bf16 v[106:109], v[142:145], v[202:205], v[106:109]
	v_mfma_f32_16x16x32_bf16 v[94:97], v[126:129], v[210:213], v[94:97]
	v_mfma_f32_16x16x32_bf16 v[90:93], v[142:145], v[210:213], v[90:93]
	v_mfma_f32_16x16x32_bf16 v[78:81], v[126:129], v[218:221], v[78:81]
	v_mfma_f32_16x16x32_bf16 v[74:77], v[142:145], v[218:221], v[74:77]
	s_setprio 0
	s_setprio 1
	v_mfma_f32_16x16x32_bf16 v[122:125], v[146:149], v[172:175], v[122:125]
	v_mfma_f32_16x16x32_bf16 v[114:117], v[154:157], v[172:175], v[114:117]
	v_mfma_f32_16x16x32_bf16 v[102:105], v[146:149], v[182:185], v[102:105]
	v_mfma_f32_16x16x32_bf16 v[98:101], v[154:157], v[182:185], v[98:101]
	v_mfma_f32_16x16x32_bf16 v[86:89], v[146:149], v[206:209], v[86:89]
	v_mfma_f32_16x16x32_bf16 v[82:85], v[154:157], v[206:209], v[82:85]
	v_mfma_f32_16x16x32_bf16 v[70:73], v[146:149], v[214:217], v[70:73]
	v_mfma_f32_16x16x32_bf16 v[66:69], v[154:157], v[214:217], v[66:69]
	v_mfma_f32_16x16x32_bf16 v[122:125], v[150:153], v[178:181], v[122:125]
	v_mfma_f32_16x16x32_bf16 v[114:117], v[168:171], v[178:181], v[114:117]
	v_mfma_f32_16x16x32_bf16 v[102:105], v[150:153], v[202:205], v[102:105]
	v_mfma_f32_16x16x32_bf16 v[98:101], v[168:171], v[202:205], v[98:101]
	v_mfma_f32_16x16x32_bf16 v[86:89], v[150:153], v[210:213], v[86:89]
	v_mfma_f32_16x16x32_bf16 v[82:85], v[168:171], v[210:213], v[82:85]
	v_mfma_f32_16x16x32_bf16 v[70:73], v[150:153], v[218:221], v[70:73]
	v_mfma_f32_16x16x32_bf16 v[66:69], v[168:171], v[218:221], v[66:69]
	s_setprio 0
	s_barrier
	s_add_i32 s86, s86, s56
	v_lshl_add_u64 v[186:187], s[50:51], 0, v[0:1]
	s_mov_b32 m0, s86
	ds_read_b128 v[172:175], v190 offset:16384
	ds_read_b128 v[178:181], v190 offset:17408
	ds_read_b128 v[182:185], v190 offset:18432
	ds_read_b128 v[202:205], v190 offset:19456
	ds_read_b128 v[206:209], v190 offset:20480
	ds_read_b128 v[210:213], v190 offset:21504
	ds_read_b128 v[214:217], v190 offset:22528
	ds_read_b128 v[218:221], v190 offset:23552
	global_load_lds_dwordx4 v[186:187], off
	s_add_i32 m0, s86, 0x2000
	s_add_u32 s86, s50, 0x80000
	v_lshl_add_u64 v[192:193], s[50:51], 0, v[158:159]
	s_addc_u32 s87, s51, 0
	s_add_i32 vcc_lo, vcc_lo, s56
	global_load_lds_dwordx4 v[192:193], off
	v_lshl_add_u64 v[222:223], s[86:87], 0, v[0:1]
	s_mov_b32 m0, vcc_lo
	v_lshl_add_u64 v[224:225], s[52:53], 0, v[160:161]
	global_load_lds_dwordx4 v[222:223], off
	v_lshl_add_u64 v[222:223], s[86:87], 0, v[158:159]
	s_add_i32 m0, vcc_lo, 0x2000
	s_nop 0
	global_load_lds_dwordx4 v[222:223], off
	v_lshl_add_u64 v[222:223], s[52:53], 0, v[162:163]
	s_mov_b32 m0, s57
	s_nop 0
	global_load_lds_dwordx4 v[222:223], off
	s_mov_b32 m0, s58
	s_nop 0
	global_load_lds_dwordx4 v[224:225], off
	s_waitcnt vmcnt(8)
	s_waitcnt lgkmcnt(0)
	s_barrier
	s_setprio 1
	s_waitcnt lgkmcnt(0)
	v_mfma_f32_16x16x32_bf16 v[62:65], v[118:121], v[172:175], v[62:65]
	v_mfma_f32_16x16x32_bf16 v[58:61], v[138:141], v[172:175], v[58:61]
	v_mfma_f32_16x16x32_bf16 v[46:49], v[118:121], v[182:185], v[46:49]
	v_mfma_f32_16x16x32_bf16 v[42:45], v[138:141], v[182:185], v[42:45]
	v_mfma_f32_16x16x32_bf16 v[30:33], v[118:121], v[206:209], v[30:33]
	v_mfma_f32_16x16x32_bf16 v[26:29], v[138:141], v[206:209], v[26:29]
	v_mfma_f32_16x16x32_bf16 v[14:17], v[118:121], v[214:217], v[14:17]
	v_mfma_f32_16x16x32_bf16 v[10:13], v[138:141], v[214:217], v[10:13]
	v_mfma_f32_16x16x32_bf16 v[62:65], v[126:129], v[178:181], v[62:65]
	v_mfma_f32_16x16x32_bf16 v[58:61], v[142:145], v[178:181], v[58:61]
	v_mfma_f32_16x16x32_bf16 v[46:49], v[126:129], v[202:205], v[46:49]
	v_mfma_f32_16x16x32_bf16 v[42:45], v[142:145], v[202:205], v[42:45]
	v_mfma_f32_16x16x32_bf16 v[30:33], v[126:129], v[210:213], v[30:33]
	v_mfma_f32_16x16x32_bf16 v[26:29], v[142:145], v[210:213], v[26:29]
	v_mfma_f32_16x16x32_bf16 v[14:17], v[126:129], v[218:221], v[14:17]
	v_mfma_f32_16x16x32_bf16 v[10:13], v[142:145], v[218:221], v[10:13]
	s_setprio 0
	s_setprio 1
	v_mfma_f32_16x16x32_bf16 v[54:57], v[146:149], v[172:175], v[54:57]
	v_mfma_f32_16x16x32_bf16 v[50:53], v[154:157], v[172:175], v[50:53]
	v_mfma_f32_16x16x32_bf16 v[38:41], v[146:149], v[182:185], v[38:41]
	v_mfma_f32_16x16x32_bf16 v[34:37], v[154:157], v[182:185], v[34:37]
	v_mfma_f32_16x16x32_bf16 v[22:25], v[146:149], v[206:209], v[22:25]
	v_mfma_f32_16x16x32_bf16 v[18:21], v[154:157], v[206:209], v[18:21]
	v_mfma_f32_16x16x32_bf16 v[6:9], v[146:149], v[214:217], v[6:9]
	v_mfma_f32_16x16x32_bf16 v[2:5], v[154:157], v[214:217], v[2:5]
	v_mfma_f32_16x16x32_bf16 v[54:57], v[150:153], v[178:181], v[54:57]
	v_mfma_f32_16x16x32_bf16 v[50:53], v[168:171], v[178:181], v[50:53]
	v_mfma_f32_16x16x32_bf16 v[38:41], v[150:153], v[202:205], v[38:41]
	v_mfma_f32_16x16x32_bf16 v[34:37], v[168:171], v[202:205], v[34:37]
	v_mfma_f32_16x16x32_bf16 v[22:25], v[150:153], v[210:213], v[22:25]
	v_mfma_f32_16x16x32_bf16 v[18:21], v[168:171], v[210:213], v[18:21]
	v_mfma_f32_16x16x32_bf16 v[6:9], v[150:153], v[218:221], v[6:9]
	v_mfma_f32_16x16x32_bf16 v[2:5], v[168:171], v[218:221], v[2:5]
	s_setprio 0
	s_barrier
	s_add_i32 s86, 0, 0x18000
	s_add_i32 s87, 0, 0x1c000
	v_add_u32_e32 v142, s86, v188
	v_add_u32_e32 v168, s87, v188
	ds_read_b128 v[118:121], v142
	ds_read_b128 v[126:129], v142 offset:1024
	ds_read_b128 v[138:141], v142 offset:2048
	ds_read_b128 v[142:145], v142 offset:3072
	ds_read_b128 v[146:149], v168
	ds_read_b128 v[150:153], v168 offset:1024
	ds_read_b128 v[154:157], v168 offset:2048
	ds_read_b128 v[168:171], v168 offset:3072
	s_add_u32 s52, s52, 0x80000
	s_addc_u32 s53, s53, 0
	s_mov_b32 m0, s59
	v_lshl_add_u64 v[226:227], s[52:53], 0, v[162:163]
	ds_read_b128 v[172:175], v190 offset:32768
	ds_read_b128 v[178:181], v190 offset:33792
	ds_read_b128 v[182:185], v190 offset:34816
	ds_read_b128 v[202:205], v190 offset:35840
	ds_read_b128 v[206:209], v190 offset:36864
	ds_read_b128 v[210:213], v190 offset:37888
	ds_read_b128 v[214:217], v190 offset:38912
	ds_read_b128 v[218:221], v190 offset:39936
	global_load_lds_dwordx4 v[226:227], off
	v_lshl_add_u64 v[226:227], s[52:53], 0, v[160:161]
	s_mov_b32 m0, s60
	s_nop 0
	global_load_lds_dwordx4 v[226:227], off
	s_waitcnt vmcnt(8)
	s_waitcnt lgkmcnt(0)
	s_barrier
	s_setprio 1
	s_waitcnt lgkmcnt(0)
	v_mfma_f32_16x16x32_bf16 v[134:137], v[118:121], v[172:175], v[134:137]
	v_mfma_f32_16x16x32_bf16 v[130:133], v[138:141], v[172:175], v[130:133]
	v_mfma_f32_16x16x32_bf16 v[110:113], v[118:121], v[182:185], v[110:113]
	v_mfma_f32_16x16x32_bf16 v[106:109], v[138:141], v[182:185], v[106:109]
	v_mfma_f32_16x16x32_bf16 v[94:97], v[118:121], v[206:209], v[94:97]
	v_mfma_f32_16x16x32_bf16 v[90:93], v[138:141], v[206:209], v[90:93]
	v_mfma_f32_16x16x32_bf16 v[78:81], v[118:121], v[214:217], v[78:81]
	v_mfma_f32_16x16x32_bf16 v[74:77], v[138:141], v[214:217], v[74:77]
	v_mfma_f32_16x16x32_bf16 v[134:137], v[126:129], v[178:181], v[134:137]
	v_mfma_f32_16x16x32_bf16 v[130:133], v[142:145], v[178:181], v[130:133]
	v_mfma_f32_16x16x32_bf16 v[110:113], v[126:129], v[202:205], v[110:113]
	v_mfma_f32_16x16x32_bf16 v[106:109], v[142:145], v[202:205], v[106:109]
	v_mfma_f32_16x16x32_bf16 v[94:97], v[126:129], v[210:213], v[94:97]
	v_mfma_f32_16x16x32_bf16 v[90:93], v[142:145], v[210:213], v[90:93]
	v_mfma_f32_16x16x32_bf16 v[78:81], v[126:129], v[218:221], v[78:81]
	v_mfma_f32_16x16x32_bf16 v[74:77], v[142:145], v[218:221], v[74:77]
	s_setprio 0
	s_setprio 1
	v_mfma_f32_16x16x32_bf16 v[122:125], v[146:149], v[172:175], v[122:125]
	v_mfma_f32_16x16x32_bf16 v[114:117], v[154:157], v[172:175], v[114:117]
	v_mfma_f32_16x16x32_bf16 v[102:105], v[146:149], v[182:185], v[102:105]
	v_mfma_f32_16x16x32_bf16 v[98:101], v[154:157], v[182:185], v[98:101]
	v_mfma_f32_16x16x32_bf16 v[86:89], v[146:149], v[206:209], v[86:89]
	v_mfma_f32_16x16x32_bf16 v[82:85], v[154:157], v[206:209], v[82:85]
	v_mfma_f32_16x16x32_bf16 v[70:73], v[146:149], v[214:217], v[70:73]
	v_mfma_f32_16x16x32_bf16 v[66:69], v[154:157], v[214:217], v[66:69]
	v_mfma_f32_16x16x32_bf16 v[122:125], v[150:153], v[178:181], v[122:125]
	v_mfma_f32_16x16x32_bf16 v[114:117], v[168:171], v[178:181], v[114:117]
	v_mfma_f32_16x16x32_bf16 v[102:105], v[150:153], v[202:205], v[102:105]
	v_mfma_f32_16x16x32_bf16 v[98:101], v[168:171], v[202:205], v[98:101]
	v_mfma_f32_16x16x32_bf16 v[86:89], v[150:153], v[210:213], v[86:89]
	v_mfma_f32_16x16x32_bf16 v[82:85], v[168:171], v[210:213], v[82:85]
	v_mfma_f32_16x16x32_bf16 v[70:73], v[150:153], v[218:221], v[70:73]
	v_mfma_f32_16x16x32_bf16 v[66:69], v[168:171], v[218:221], v[66:69]
	s_setprio 0
	s_barrier
	s_add_i32 s52, s86, s56
	v_lshl_add_u64 v[186:187], v[186:187], 0, s[88:89]
	s_mov_b32 m0, s52
	ds_read_b128 v[172:175], v190 offset:49152
	ds_read_b128 v[178:181], v190 offset:50176
	ds_read_b128 v[182:185], v190 offset:51200
	ds_read_b128 v[202:205], v190 offset:52224
	ds_read_b128 v[206:209], v190 offset:53248
	ds_read_b128 v[210:213], v190 offset:54272
	ds_read_b128 v[214:217], v190 offset:55296
	ds_read_b128 v[218:221], v190 offset:56320
	global_load_lds_dwordx4 v[186:187], off
	s_add_i32 m0, s52, 0x2000
	s_add_u32 s50, s50, 0x80080
	v_lshl_add_u64 v[186:187], v[192:193], 0, s[88:89]
	s_addc_u32 s51, s51, 0
	s_add_i32 s52, s87, s56
	global_load_lds_dwordx4 v[186:187], off
	v_lshl_add_u64 v[186:187], s[50:51], 0, v[0:1]
	s_mov_b32 m0, s52
	s_nop 0
	global_load_lds_dwordx4 v[186:187], off
	v_lshl_add_u64 v[186:187], s[50:51], 0, v[158:159]
	s_add_i32 m0, s52, 0x2000
	s_nop 0
	global_load_lds_dwordx4 v[186:187], off
	v_lshl_add_u64 v[186:187], v[222:223], 0, s[88:89]
	s_mov_b32 m0, s14
	s_nop 0
	global_load_lds_dwordx4 v[186:187], off
	v_lshl_add_u64 v[186:187], v[224:225], 0, s[88:89]
	s_mov_b32 m0, s62
	s_nop 0
	global_load_lds_dwordx4 v[186:187], off
	s_waitcnt vmcnt(8)
	s_waitcnt lgkmcnt(0)
	s_barrier
	s_setprio 1
	s_waitcnt lgkmcnt(0)
	v_mfma_f32_16x16x32_bf16 v[62:65], v[118:121], v[172:175], v[62:65]
	v_mfma_f32_16x16x32_bf16 v[58:61], v[138:141], v[172:175], v[58:61]
	v_mfma_f32_16x16x32_bf16 v[46:49], v[118:121], v[182:185], v[46:49]
	v_mfma_f32_16x16x32_bf16 v[42:45], v[138:141], v[182:185], v[42:45]
	v_mfma_f32_16x16x32_bf16 v[30:33], v[118:121], v[206:209], v[30:33]
	v_mfma_f32_16x16x32_bf16 v[26:29], v[138:141], v[206:209], v[26:29]
	v_mfma_f32_16x16x32_bf16 v[14:17], v[118:121], v[214:217], v[14:17]
	v_mfma_f32_16x16x32_bf16 v[10:13], v[138:141], v[214:217], v[10:13]
	v_mfma_f32_16x16x32_bf16 v[62:65], v[126:129], v[178:181], v[62:65]
	v_mfma_f32_16x16x32_bf16 v[58:61], v[142:145], v[178:181], v[58:61]
	v_mfma_f32_16x16x32_bf16 v[46:49], v[126:129], v[202:205], v[46:49]
	v_mfma_f32_16x16x32_bf16 v[42:45], v[142:145], v[202:205], v[42:45]
	v_mfma_f32_16x16x32_bf16 v[30:33], v[126:129], v[210:213], v[30:33]
	v_mfma_f32_16x16x32_bf16 v[26:29], v[142:145], v[210:213], v[26:29]
	v_mfma_f32_16x16x32_bf16 v[14:17], v[126:129], v[218:221], v[14:17]
	v_mfma_f32_16x16x32_bf16 v[10:13], v[142:145], v[218:221], v[10:13]
	s_setprio 0
	s_setprio 1
	v_mfma_f32_16x16x32_bf16 v[54:57], v[146:149], v[172:175], v[54:57]
	v_mfma_f32_16x16x32_bf16 v[50:53], v[154:157], v[172:175], v[50:53]
	v_mfma_f32_16x16x32_bf16 v[38:41], v[146:149], v[182:185], v[38:41]
	v_mfma_f32_16x16x32_bf16 v[34:37], v[154:157], v[182:185], v[34:37]
	v_mfma_f32_16x16x32_bf16 v[22:25], v[146:149], v[206:209], v[22:25]
	v_mfma_f32_16x16x32_bf16 v[18:21], v[154:157], v[206:209], v[18:21]
	v_mfma_f32_16x16x32_bf16 v[6:9], v[146:149], v[214:217], v[6:9]
	v_mfma_f32_16x16x32_bf16 v[2:5], v[154:157], v[214:217], v[2:5]
	v_mfma_f32_16x16x32_bf16 v[54:57], v[150:153], v[178:181], v[54:57]
	v_mfma_f32_16x16x32_bf16 v[50:53], v[168:171], v[178:181], v[50:53]
	v_mfma_f32_16x16x32_bf16 v[38:41], v[150:153], v[202:205], v[38:41]
	v_mfma_f32_16x16x32_bf16 v[34:37], v[168:171], v[202:205], v[34:37]
	v_mfma_f32_16x16x32_bf16 v[22:25], v[150:153], v[210:213], v[22:25]
	v_mfma_f32_16x16x32_bf16 v[18:21], v[168:171], v[210:213], v[18:21]
	v_mfma_f32_16x16x32_bf16 v[6:9], v[150:153], v[218:221], v[6:9]
	v_mfma_f32_16x16x32_bf16 v[2:5], v[168:171], v[218:221], v[2:5]
	s_setprio 0
	s_add_i32 s77, s77, 2
	s_add_u32 s4, s4, 0x100
	s_addc_u32 s5, s5, 0
	s_add_u32 s67, s67, 0x100
	s_addc_u32 s76, s76, 0
	s_cmp_gt_u32 s77, 29
	s_barrier
	s_cbranch_scc0 .LBB0_578
	s_and_b64 vcc, exec, s[36:37]
	s_cbranch_vccz .LBB0_581
	s_barrier
